# speedup vs baseline: 1.0428x; 1.0022x over previous
; #define p_ssq2 W_(float, OFF_SSQ2)
; __global__ void __launch_bounds__(512) fwd_megakernel(Params p) {
;     ...
;   for (int rep_ = 0; rep_ < REP7; ++rep_) {
;     f32x4 g[2][2];
;     #pragma unroll
;     for (int c = 0; c < 2; ++c)
;       #pragma unroll
;       for (int h = 0; h < 2; ++h) g[c][h] = *reinterpret_cast<const f32x4*>(p.fin_g + c * 512 + lane * 8 + h * 4);
;     for (int row0 = (blockIdx.x * 8 + wid) * 4; row0 < TC; row0 += G * 32) {
;       u32x4 hv[4][2]; f32x4 s4[4];
;       #pragma unroll
;       for (int r = 0; r < 4; ++r) {
;         s4[r] = *reinterpret_cast<const f32x4*>(p_ssq2 + (long)(row0 + r) * 4);
;         #pragma unroll
;         for (int c = 0; c < 2; ++c) hv[r][c] = *reinterpret_cast<const u32x4*>(p_h2b + (long)(row0 + r) * DM + c * 512 + lane * 8);
;       }
;       #pragma unroll
;       for (int r = 0; r < 4; ++r) {
;         const float rs = rsqrtf(((s4[r][0] + s4[r][1]) + (s4[r][2] + s4[r][3])) * (1.f / DM) + EPS);
.LBB0_806:
	s_or_b64 exec, exec, s[0:1]
	v_lshl_add_u32 v16, s76, 5, v144
	s_mov_b32 s0, 0x18000
	v_cmp_gt_i32_e32 vcc, s0, v16
	s_barrier
	s_and_saveexec_b64 s[0:1], vcc
	s_cbranch_execz .LBB0_809
	v_lshlrev_b32_e32 v17, 5, v193
	global_load_dwordx4 v[0:3], v17, s[56:57] offset:16
	global_load_dwordx4 v[4:7], v17, s[56:57]
	global_load_dwordx4 v[8:11], v17, s[56:57] offset:2064
	global_load_dwordx4 v[12:15], v17, s[56:57] offset:2048
	v_ashrrev_i32_e32 v17, 31, v16
	s_lshl_b32 s6, s94, 5
	v_lshlrev_b64 v[18:19], 12, v[16:17]
	v_lshl_or_b32 v18, v193, 5, v18
	s_ashr_i32 s7, s6, 31
	v_lshlrev_b64 v[22:23], 11, v[16:17]
	s_mov_b32 s0, 0x358637bd
	v_lshl_add_u64 v[18:19], s[58:59], 0, v[18:19]
	s_lshl_b64 s[8:9], s[6:7], 12
	v_lshlrev_b64 v[20:21], 4, v[16:17]
	s_lshl_b64 s[10:11], s[6:7], 4
	v_lshl_or_b32 v22, v193, 4, v22
	s_lshl_b64 s[12:13], s[6:7], 11
	s_mov_b64 s[14:15], 0
	s_mov_b64 s[16:17], 0x2eb02400
	s_mov_b32 s7, 0x21000000
	s_mov_b32 s19, 0x21001000
	s_mov_b32 s18, 0x3a800000
	s_mov_b32 s20, 0x800000
	s_movk_i32 s21, 0x1000
	s_movk_i32 s22, 0x2000
	s_movk_i32 s23, 0x3000
	s_mov_b32 s24, 0x17fff
	v_mov_b64_e32 v[24:25], s[0:1]
	s_mov_b64 s[40:41], 0x21000000
	s_mov_b64 s[42:43], 0x21001000
	v_lshl_add_u64 v[160:161], s[34:35], 0, v[20:21]
	v_lshl_add_u64 v[164:165], s[34:35], 0, v[22:23]
	v_lshl_add_u64 v[162:163], v[160:161], 0, s[16:17]
	v_lshl_add_u64 v[166:167], v[164:165], 0, s[40:41]
	v_lshl_add_u64 v[168:169], v[164:165], 0, s[42:43]
	global_load_dwordx4 v[200:203], v[162:163], off offset:32
	global_load_dwordx4 v[204:207], v[162:163], off offset:16
	global_load_dwordx4 v[208:211], v[162:163], off
	global_load_dwordx4 v[212:215], v[162:163], off offset:48
	global_load_dwordx4 v[216:219], v[166:167], off offset:1024
	global_load_dwordx4 v[220:223], v[166:167], off offset:2048
	global_load_dwordx4 v[224:227], v[168:169], off offset:-4096
	global_load_dwordx4 v[228:231], v[166:167], off offset:3072
	global_load_dwordx4 v[232:235], v[168:169], off
	global_load_dwordx4 v[236:239], v[168:169], off offset:1024
	global_load_dwordx4 v[240:243], v[168:169], off offset:2048
	global_load_dwordx4 v[244:247], v[168:169], off offset:3072
	v_lshl_add_u64 v[20:21], v[20:21], 0, s[10:11]
	v_lshl_add_u64 v[22:23], v[22:23], 0, s[12:13]
	s_waitcnt vmcnt(0)
	s_branch .Lp7_body
.LBB0_808:
	s_waitcnt vmcnt(16)
.Lp7_body:
	v_mov_b64_e32 v[36:37], v[200:201]
	v_mov_b64_e32 v[38:39], v[202:203]
	v_mov_b64_e32 v[40:41], v[204:205]
	v_mov_b64_e32 v[42:43], v[206:207]
	v_mov_b64_e32 v[44:45], v[208:209]
	v_mov_b64_e32 v[46:47], v[210:211]
	v_mov_b64_e32 v[48:49], v[212:213]
	v_mov_b64_e32 v[50:51], v[214:215]
	v_mov_b64_e32 v[52:53], v[216:217]
	v_mov_b64_e32 v[54:55], v[218:219]
	v_mov_b64_e32 v[56:57], v[220:221]
	v_mov_b64_e32 v[58:59], v[222:223]
	v_mov_b64_e32 v[30:31], v[224:225]
	v_mov_b64_e32 v[32:33], v[226:227]
	v_mov_b64_e32 v[60:61], v[228:229]
	v_mov_b64_e32 v[62:63], v[230:231]
	v_mov_b64_e32 v[64:65], v[232:233]
	v_mov_b64_e32 v[66:67], v[234:235]
	v_mov_b64_e32 v[68:69], v[236:237]
	v_mov_b64_e32 v[70:71], v[238:239]
	v_mov_b64_e32 v[72:73], v[240:241]
	v_mov_b64_e32 v[74:75], v[242:243]
	v_mov_b64_e32 v[76:77], v[244:245]
	v_mov_b64_e32 v[78:79], v[246:247]
	v_add_co_u32_e32 v26, vcc, s21, v18
	s_nop 1
	v_addc_co_u32_e32 v27, vcc, 0, v19, vcc
	v_add_co_u32_e32 v28, vcc, s22, v18
	s_nop 1
	v_addc_co_u32_e32 v29, vcc, 0, v19, vcc
	v_add_co_u32_e32 v34, vcc, s23, v18
	s_nop 1
	v_addc_co_u32_e32 v35, vcc, 0, v19, vcc
	v_add_u32_e32 v16, s6, v16
	v_cmp_lt_i32_e64 s[0:1], s24, v16
	s_or_b64 s[14:15], s[0:1], s[14:15]
	v_lshl_add_u64 v[160:161], s[34:35], 0, v[20:21]
	v_lshl_add_u64 v[164:165], s[34:35], 0, v[22:23]
	v_lshl_add_u64 v[162:163], v[160:161], 0, s[16:17]
	v_lshl_add_u64 v[166:167], v[164:165], 0, s[40:41]
	v_lshl_add_u64 v[168:169], v[164:165], 0, s[42:43]
	global_load_dwordx4 v[200:203], v[162:163], off offset:32
	global_load_dwordx4 v[204:207], v[162:163], off offset:16
	global_load_dwordx4 v[208:211], v[162:163], off
	global_load_dwordx4 v[212:215], v[162:163], off offset:48
	global_load_dwordx4 v[216:219], v[166:167], off offset:1024
	global_load_dwordx4 v[220:223], v[166:167], off offset:2048
	global_load_dwordx4 v[224:227], v[168:169], off offset:-4096
	global_load_dwordx4 v[228:231], v[166:167], off offset:3072
	global_load_dwordx4 v[232:235], v[168:169], off
	global_load_dwordx4 v[236:239], v[168:169], off offset:1024
	global_load_dwordx4 v[240:243], v[168:169], off offset:2048
	global_load_dwordx4 v[244:247], v[168:169], off offset:3072
	v_lshl_add_u64 v[20:21], v[20:21], 0, s[10:11]
	v_lshl_add_u64 v[22:23], v[22:23], 0, s[12:13]
	v_mov_b32_e32 v80, v41
	v_mov_b32_e32 v81, v42
	v_mov_b32_e32 v41, v43
	v_mov_b32_e32 v42, v37
	v_mov_b32_e32 v43, v38
	v_mov_b32_e32 v37, v39
	v_mov_b32_e32 v38, v45
	v_mov_b32_e32 v39, v46
	v_mov_b32_e32 v45, v47
	v_pk_add_f32 v[40:41], v[80:81], v[40:41]
	v_pk_add_f32 v[36:37], v[42:43], v[36:37]
	v_mov_b32_e32 v42, v49
	v_mov_b32_e32 v43, v50
	v_mov_b32_e32 v49, v51
	v_pk_add_f32 v[38:39], v[38:39], v[44:45]
	v_lshlrev_b32_e32 v44, 16, v52
	v_and_b32_e32 v45, 0xffff0000, v52
	v_lshlrev_b32_e32 v46, 16, v53
	v_and_b32_e32 v47, 0xffff0000, v53
	v_lshlrev_b32_e32 v50, 16, v54
	v_and_b32_e32 v51, 0xffff0000, v54
	v_lshlrev_b32_e32 v52, 16, v55
	v_and_b32_e32 v53, 0xffff0000, v55
	v_mov_b32_e32 v54, v40
	v_pk_add_f32 v[42:43], v[42:43], v[48:49]
	v_mov_b32_e32 v55, v38
	v_mov_b32_e32 v38, v41
	v_mov_b32_e32 v49, v36
	v_mov_b32_e32 v48, v42
	v_mov_b32_e32 v36, v43
	v_pk_add_f32 v[38:39], v[54:55], v[38:39]
	v_pk_add_f32 v[36:37], v[48:49], v[36:37]
	v_pk_fma_f32 v[38:39], v[38:39], s[18:19], v[24:25] op_sel_hi:[1,0,0]
; #define p_ssq2 W_(float, OFF_SSQ2)
; __global__ void __launch_bounds__(512) fwd_megakernel(Params p) {
;     ...
;         s4[r] = *reinterpret_cast<const f32x4*>(p_ssq2 + (long)(row0 + r) * 4);
;         #pragma unroll
;         for (int c = 0; c < 2; ++c) hv[r][c] = *reinterpret_cast<const u32x4*>(p_h2b + (long)(row0 + r) * DM + c * 512 + lane * 8);
;       }
;       #pragma unroll
;       for (int r = 0; r < 4; ++r) {
;         const float rs = rsqrtf(((s4[r][0] + s4[r][1]) + (s4[r][2] + s4[r][3])) * (1.f / DM) + EPS);
;         #pragma unroll
;         for (int c = 0; c < 2; ++c) {
;           const u32x4 w = hv[r][c];
;           f32x4 lo = {__uint_as_float(w[0] << 16), __uint_as_float(w[0] & 0xffff0000u), __uint_as_float(w[1] << 16), __uint_as_float(w[1] & 0xffff0000u)};
;           f32x4 hi = {__uint_as_float(w[2] << 16), __uint_as_float(w[2] & 0xffff0000u), __uint_as_float(w[3] << 16), __uint_as_float(w[3] & 0xffff0000u)};
	v_pk_fma_f32 v[36:37], v[36:37], s[18:19], v[24:25] op_sel_hi:[1,0,0]
	v_mul_f32_e32 v17, 0x4b800000, v39
	v_cmp_gt_f32_e64 s[4:5], s20, v39
	v_mul_f32_e32 v48, 0x4b800000, v38
	v_cmp_gt_f32_e32 vcc, s20, v38
	v_mul_f32_e32 v49, 0x4b800000, v37
	v_mul_f32_e32 v54, 0x4b800000, v36
	v_cmp_gt_f32_e64 s[0:1], s20, v36
	v_cmp_gt_f32_e64 s[2:3], s20, v37
	v_cndmask_b32_e64 v17, v39, v17, s[4:5]
	v_cndmask_b32_e32 v38, v38, v48, vcc
	v_cndmask_b32_e64 v37, v37, v49, s[2:3]
	v_cndmask_b32_e64 v36, v36, v54, s[0:1]
	v_rsq_f32_e32 v17, v17
	v_rsq_f32_e32 v38, v38
	v_rsq_f32_e32 v37, v37
	v_rsq_f32_e32 v39, v36
	v_mul_f32_e32 v36, 0x45800000, v17
	v_lshlrev_b32_e32 v84, 16, v30
	v_and_b32_e32 v85, 0xffff0000, v30
	v_lshlrev_b32_e32 v30, 16, v31
	v_and_b32_e32 v31, 0xffff0000, v31
	v_mul_f32_e32 v48, 0x45800000, v38
	v_mul_f32_e32 v49, 0x45800000, v37
	v_mul_f32_e32 v54, 0x45800000, v39
	v_cndmask_b32_e64 v36, v17, v36, s[4:5]
	v_lshlrev_b32_e32 v80, 16, v56
	v_and_b32_e32 v81, 0xffff0000, v56
	v_lshlrev_b32_e32 v56, 16, v57
	v_and_b32_e32 v57, 0xffff0000, v57
	v_lshlrev_b32_e32 v82, 16, v58
	v_and_b32_e32 v83, 0xffff0000, v58
	v_lshlrev_b32_e32 v58, 16, v59
	v_and_b32_e32 v59, 0xffff0000, v59
	v_lshlrev_b32_e32 v86, 16, v32
	v_and_b32_e32 v87, 0xffff0000, v32
	v_lshlrev_b32_e32 v32, 16, v33
	v_and_b32_e32 v33, 0xffff0000, v33
	v_lshlrev_b32_e32 v40, 16, v60
	v_and_b32_e32 v41, 0xffff0000, v60
	v_lshlrev_b32_e32 v60, 16, v61
	v_and_b32_e32 v61, 0xffff0000, v61
	v_lshlrev_b32_e32 v88, 16, v62
	v_and_b32_e32 v89, 0xffff0000, v62
	v_lshlrev_b32_e32 v62, 16, v63
	v_and_b32_e32 v63, 0xffff0000, v63
	v_lshlrev_b32_e32 v90, 16, v64
	v_and_b32_e32 v91, 0xffff0000, v64
	v_lshlrev_b32_e32 v64, 16, v65
	v_and_b32_e32 v65, 0xffff0000, v65
	v_lshlrev_b32_e32 v92, 16, v66
	v_and_b32_e32 v93, 0xffff0000, v66
	v_lshlrev_b32_e32 v66, 16, v67
	v_and_b32_e32 v67, 0xffff0000, v67
	v_lshlrev_b32_e32 v94, 16, v68
	v_and_b32_e32 v95, 0xffff0000, v68
	v_lshlrev_b32_e32 v68, 16, v69
	v_and_b32_e32 v69, 0xffff0000, v69
	v_lshlrev_b32_e32 v96, 16, v70
	v_and_b32_e32 v97, 0xffff0000, v70
	v_lshlrev_b32_e32 v70, 16, v71
	v_and_b32_e32 v71, 0xffff0000, v71
	v_lshlrev_b32_e32 v42, 16, v72
	v_and_b32_e32 v43, 0xffff0000, v72
	v_lshlrev_b32_e32 v72, 16, v73
	v_and_b32_e32 v73, 0xffff0000, v73
	v_lshlrev_b32_e32 v98, 16, v74
	v_and_b32_e32 v99, 0xffff0000, v74
	v_lshlrev_b32_e32 v74, 16, v75
	v_and_b32_e32 v75, 0xffff0000, v75
	v_lshlrev_b32_e32 v100, 16, v76
	v_and_b32_e32 v101, 0xffff0000, v76
	v_lshlrev_b32_e32 v76, 16, v77
	v_and_b32_e32 v77, 0xffff0000, v77
	v_lshlrev_b32_e32 v102, 16, v78
	v_and_b32_e32 v103, 0xffff0000, v78
	v_lshlrev_b32_e32 v78, 16, v79
	v_and_b32_e32 v79, 0xffff0000, v79
	v_cndmask_b32_e32 v38, v38, v48, vcc
	v_cndmask_b32_e64 v48, v37, v49, s[2:3]
	v_cndmask_b32_e64 v54, v39, v54, s[0:1]
	v_pk_mul_f32 v[84:85], v[36:37], v[84:85] op_sel_hi:[0,1]
	v_pk_mul_f32 v[30:31], v[36:37], v[30:31] op_sel_hi:[0,1]
	v_pk_mul_f32 v[86:87], v[36:37], v[86:87] op_sel_hi:[0,1]
	v_pk_mul_f32 v[104:105], v[36:37], v[32:33] op_sel_hi:[0,1]
	v_pk_mul_f32 v[44:45], v[36:37], v[44:45] op_sel_hi:[0,1]
	v_pk_mul_f32 v[46:47], v[36:37], v[46:47] op_sel_hi:[0,1]
	v_pk_mul_f32 v[50:51], v[36:37], v[50:51] op_sel_hi:[0,1]
	v_pk_mul_f32 v[52:53], v[36:37], v[52:53] op_sel_hi:[0,1]
	v_pk_mul_f32 v[80:81], v[38:39], v[80:81] op_sel_hi:[0,1]
	v_pk_mul_f32 v[56:57], v[38:39], v[56:57] op_sel_hi:[0,1]
	v_pk_mul_f32 v[82:83], v[38:39], v[82:83] op_sel_hi:[0,1]
	v_pk_mul_f32 v[58:59], v[38:39], v[58:59] op_sel_hi:[0,1]
; __global__ void __launch_bounds__(512) fwd_megakernel(Params p) {
;     ...
;         for (int c = 0; c < 2; ++c) {
;           const u32x4 w = hv[r][c];
;           f32x4 lo = {__uint_as_float(w[0] << 16), __uint_as_float(w[0] & 0xffff0000u), __uint_as_float(w[1] << 16), __uint_as_float(w[1] & 0xffff0000u)};
;           f32x4 hi = {__uint_as_float(w[2] << 16), __uint_as_float(w[2] & 0xffff0000u), __uint_as_float(w[3] << 16), __uint_as_float(w[3] & 0xffff0000u)};
;           float* o = p.out + (long)(row0 + r) * DM + c * 512 + lane * 8;
;           *reinterpret_cast<f32x4*>(o) = lo * rs * g[c][0];
;           *reinterpret_cast<f32x4*>(o + 4) = hi * rs * g[c][1];
;         }
;       }
	v_pk_mul_f32 v[106:107], v[38:39], v[40:41] op_sel_hi:[0,1]
	v_pk_mul_f32 v[60:61], v[38:39], v[60:61] op_sel_hi:[0,1]
	v_pk_mul_f32 v[88:89], v[38:39], v[88:89] op_sel_hi:[0,1]
	v_pk_mul_f32 v[62:63], v[38:39], v[62:63] op_sel_hi:[0,1]
	v_pk_mul_f32 v[90:91], v[48:49], v[90:91] op_sel_hi:[0,1]
	v_pk_mul_f32 v[64:65], v[48:49], v[64:65] op_sel_hi:[0,1]
	v_pk_mul_f32 v[92:93], v[48:49], v[92:93] op_sel_hi:[0,1]
	v_pk_mul_f32 v[108:109], v[48:49], v[66:67] op_sel_hi:[0,1]
	v_pk_mul_f32 v[94:95], v[48:49], v[94:95] op_sel_hi:[0,1]
	v_pk_mul_f32 v[110:111], v[48:49], v[68:69] op_sel_hi:[0,1]
	v_pk_mul_f32 v[96:97], v[48:49], v[96:97] op_sel_hi:[0,1]
	v_pk_mul_f32 v[112:113], v[48:49], v[70:71] op_sel_hi:[0,1]
	v_pk_mul_f32 v[114:115], v[54:55], v[42:43] op_sel_hi:[0,1]
	v_pk_mul_f32 v[116:117], v[54:55], v[72:73] op_sel_hi:[0,1]
	v_pk_mul_f32 v[98:99], v[54:55], v[98:99] op_sel_hi:[0,1]
	v_pk_mul_f32 v[118:119], v[54:55], v[74:75] op_sel_hi:[0,1]
	v_pk_mul_f32 v[100:101], v[54:55], v[100:101] op_sel_hi:[0,1]
	v_pk_mul_f32 v[120:121], v[54:55], v[76:77] op_sel_hi:[0,1]
	v_pk_mul_f32 v[102:103], v[54:55], v[102:103] op_sel_hi:[0,1]
	v_pk_mul_f32 v[122:123], v[54:55], v[78:79] op_sel_hi:[0,1]
	v_pk_mul_f32 v[32:33], v[6:7], v[30:31]
	v_pk_mul_f32 v[30:31], v[4:5], v[84:85]
	v_pk_mul_f32 v[38:39], v[2:3], v[104:105]
	v_pk_mul_f32 v[36:37], v[0:1], v[86:87]
	v_pk_mul_f32 v[42:43], v[14:15], v[46:47]
	v_pk_mul_f32 v[40:41], v[12:13], v[44:45]
	v_pk_mul_f32 v[46:47], v[10:11], v[52:53]
	v_pk_mul_f32 v[44:45], v[8:9], v[50:51]
	v_pk_mul_f32 v[50:51], v[6:7], v[56:57]
	v_pk_mul_f32 v[48:49], v[4:5], v[80:81]
	v_pk_mul_f32 v[54:55], v[2:3], v[58:59]
	v_pk_mul_f32 v[52:53], v[0:1], v[82:83]
	v_pk_mul_f32 v[58:59], v[14:15], v[60:61]
	v_pk_mul_f32 v[56:57], v[12:13], v[106:107]
	v_pk_mul_f32 v[62:63], v[10:11], v[62:63]
	v_pk_mul_f32 v[60:61], v[8:9], v[88:89]
	v_pk_mul_f32 v[66:67], v[6:7], v[64:65]
	v_pk_mul_f32 v[64:65], v[4:5], v[90:91]
	v_pk_mul_f32 v[70:71], v[2:3], v[108:109]
	v_pk_mul_f32 v[68:69], v[0:1], v[92:93]
	v_pk_mul_f32 v[74:75], v[14:15], v[110:111]
	v_pk_mul_f32 v[72:73], v[12:13], v[94:95]
	v_pk_mul_f32 v[78:79], v[10:11], v[112:113]
	v_pk_mul_f32 v[76:77], v[8:9], v[96:97]
	v_pk_mul_f32 v[82:83], v[6:7], v[116:117]
	v_pk_mul_f32 v[80:81], v[4:5], v[114:115]
	v_pk_mul_f32 v[86:87], v[2:3], v[118:119]
	v_pk_mul_f32 v[84:85], v[0:1], v[98:99]
	v_pk_mul_f32 v[90:91], v[14:15], v[120:121]
	v_pk_mul_f32 v[88:89], v[12:13], v[100:101]
	v_pk_mul_f32 v[94:95], v[10:11], v[122:123]
	v_pk_mul_f32 v[92:93], v[8:9], v[102:103]
	global_store_dwordx4 v[18:19], v[30:33], off
	global_store_dwordx4 v[18:19], v[36:39], off offset:16
	global_store_dwordx4 v[18:19], v[40:43], off offset:2048
	global_store_dwordx4 v[18:19], v[44:47], off offset:2064
	global_store_dwordx4 v[28:29], v[48:51], off offset:-4096
	global_store_dwordx4 v[26:27], v[52:55], off offset:16
	global_store_dwordx4 v[26:27], v[56:59], off offset:2048
	global_store_dwordx4 v[26:27], v[60:63], off offset:2064
	global_store_dwordx4 v[28:29], v[64:67], off
	global_store_dwordx4 v[28:29], v[68:71], off offset:16
	global_store_dwordx4 v[28:29], v[72:75], off offset:2048
	global_store_dwordx4 v[28:29], v[76:79], off offset:2064
	global_store_dwordx4 v[34:35], v[80:83], off
	global_store_dwordx4 v[34:35], v[84:87], off offset:16
	global_store_dwordx4 v[34:35], v[88:91], off offset:2048
	global_store_dwordx4 v[34:35], v[92:95], off offset:2064
	v_lshl_add_u64 v[18:19], v[18:19], 0, s[8:9]
	s_andn2_b64 exec, exec, s[14:15]
	s_cbranch_execnz .LBB0_808
